# sc1 write-through on P0's 16-byte transposed weight-convert stores, on top of the LN row-store write-through
# baseline (speedup 1.0000x reference)
.LBB0_27:
	s_cmp_gt_i32 s68, 0x157ff
	s_mov_b64 s[4:5], -1
	s_cbranch_scc0 .LBB0_48
	s_cmp_gt_u32 s68, 0x1747f
	s_cbranch_scc0 .LBB0_42
	s_cmp_gt_u32 s68, 0x17a7f
	s_cbranch_scc0 .LBB0_39
	s_cmp_gt_u32 s68, 0x17e7f
	s_cbranch_scc0 .LBB0_36
	s_cmp_gt_u32 s68, 0x1807f
	s_cbranch_scc0 .LBB0_33
	s_add_i32 s0, s68, 0xfffe7f80
	s_and_b32 s62, s33, 0xfe0
	s_lshr_b32 s0, s0, 1
	s_and_b32 s0, s0, 0x7fffffc0
	s_lshl_b32 s4, s62, 12
	v_readlane_b32 s5, v254, 11
	s_add_u32 s8, s5, s4
	v_readlane_b32 s4, v254, 12
	s_addc_u32 s9, s4, 0
	s_lshl_b64 s[4:5], s[0:1], 14
	s_add_u32 s4, s26, s4
	s_addc_u32 s5, s27, s5
	s_lshl_b32 s62, s62, 2
	s_add_u32 s4, s4, s62
	s_addc_u32 s5, s5, 0
	s_add_u32 s62, s4, 0x8000
	s_addc_u32 s63, s5, 0
	global_load_dword v19, v26, s[4:5] nt
	global_load_dword v21, v26, s[62:63] nt
	s_add_u32 s62, s4, 0x10000
	s_addc_u32 s63, s5, 0
	global_load_dword v23, v26, s[62:63] nt
	s_add_u32 s62, s4, 0x18000
	s_addc_u32 s63, s5, 0
	global_load_dword v25, v26, s[62:63] nt
	s_add_u32 s62, s4, 0x20000
	s_addc_u32 s63, s5, 0
	global_load_dword v42, v26, s[62:63] nt
	s_add_u32 s62, s4, 0x28000
	s_addc_u32 s63, s5, 0
	global_load_dword v43, v26, s[62:63] nt
	s_add_u32 s62, s4, 0x30000
	s_addc_u32 s63, s5, 0
	global_load_dword v44, v26, s[62:63] nt
	s_add_u32 s62, s4, 0x38000
	s_addc_u32 s63, s5, 0
	global_load_dword v45, v26, s[62:63] nt
	s_add_u32 s62, s4, 0x40000
	s_addc_u32 s63, s5, 0
	global_load_dword v46, v26, s[62:63] nt
	s_add_u32 s62, s4, 0x48000
	s_addc_u32 s63, s5, 0
	global_load_dword v47, v26, s[62:63] nt
	s_add_u32 s62, s4, 0x50000
	s_addc_u32 s63, s5, 0
	global_load_dword v48, v26, s[62:63] nt
	s_add_u32 s62, s4, 0x58000
	s_addc_u32 s63, s5, 0
	global_load_dword v49, v26, s[62:63] nt
	s_add_u32 s62, s4, 0x60000
	s_addc_u32 s63, s5, 0
	global_load_dword v50, v26, s[62:63] nt
	s_add_u32 s62, s4, 0x68000
	s_addc_u32 s63, s5, 0
	global_load_dword v51, v26, s[62:63] nt
	s_add_u32 s62, s4, 0x70000
	s_addc_u32 s63, s5, 0
	global_load_dword v52, v26, s[62:63] nt
	s_add_u32 s62, s4, 0x78000
	s_addc_u32 s63, s5, 0
	global_load_dword v53, v26, s[62:63] nt
	s_add_u32 s62, s4, 0x80000
	s_addc_u32 s63, s5, 0
	global_load_dword v54, v26, s[62:63] nt
	s_add_u32 s62, s4, 0x88000
	s_addc_u32 s63, s5, 0
	global_load_dword v55, v26, s[62:63] nt
	s_add_u32 s62, s4, 0x90000
	s_addc_u32 s63, s5, 0
	global_load_dword v56, v26, s[62:63] nt
	s_add_u32 s62, s4, 0x98000
	s_addc_u32 s63, s5, 0
	global_load_dword v57, v26, s[62:63] nt
	s_add_u32 s62, s4, 0xa0000
	s_addc_u32 s63, s5, 0
	global_load_dword v58, v26, s[62:63] nt
	s_add_u32 s62, s4, 0xa8000
	s_addc_u32 s63, s5, 0
	global_load_dword v59, v26, s[62:63] nt
	s_add_u32 s62, s4, 0xb0000
	s_addc_u32 s63, s5, 0
	global_load_dword v60, v26, s[62:63] nt
	s_add_u32 s62, s4, 0xb8000
	s_addc_u32 s63, s5, 0
	global_load_dword v61, v26, s[62:63] nt
	s_add_u32 s62, s4, 0xc0000
	s_addc_u32 s63, s5, 0
	global_load_dword v62, v26, s[62:63] nt
	s_add_u32 s62, s4, 0xc8000
	s_addc_u32 s63, s5, 0
	global_load_dword v63, v26, s[62:63] nt
	s_add_u32 s62, s4, 0xd0000
	s_addc_u32 s63, s5, 0
	global_load_dword v64, v26, s[62:63] nt
	s_add_u32 s62, s4, 0xd8000
	s_addc_u32 s63, s5, 0
	global_load_dword v65, v26, s[62:63] nt
	s_add_u32 s62, s4, 0xe0000
	s_addc_u32 s63, s5, 0
	global_load_dword v66, v26, s[62:63] nt
	s_add_u32 s62, s4, 0xe8000
	s_addc_u32 s63, s5, 0
	global_load_dword v67, v26, s[62:63] nt
	s_add_u32 s62, s4, 0xf0000
	s_addc_u32 s63, s5, 0
	s_add_u32 s4, s4, 0xf8000
	global_load_dword v68, v26, s[62:63] nt
	s_addc_u32 s5, s5, 0
	global_load_dword v69, v26, s[4:5] nt
	s_waitcnt vmcnt(0)
	s_add_u32 s4, s8, s0
	ds_write2_b32 v30, v19, v21 offset1:66
	ds_write2_b32 v30, v23, v25 offset0:132 offset1:198
	ds_write2_b32 v34, v42, v43 offset0:8 offset1:74
	ds_write2_b32 v34, v44, v45 offset0:140 offset1:206
	ds_write2_b32 v35, v46, v47 offset0:16 offset1:82
	ds_write2_b32 v35, v48, v49 offset0:148 offset1:214
	ds_write2_b32 v36, v50, v51 offset0:24 offset1:90
	ds_write2_b32 v36, v52, v53 offset0:156 offset1:222
	ds_write2_b32 v37, v54, v55 offset0:32 offset1:98
	ds_write2_b32 v37, v56, v57 offset0:164 offset1:230
	ds_write2_b32 v38, v58, v59 offset0:40 offset1:106
	ds_write2_b32 v38, v60, v61 offset0:172 offset1:238
	ds_write2_b32 v39, v62, v63 offset0:48 offset1:114
	ds_write2_b32 v39, v64, v65 offset0:180 offset1:246
	ds_write2_b32 v40, v66, v67 offset0:56 offset1:122
	ds_write2_b32 v40, v68, v69 offset0:188 offset1:254
	s_waitcnt lgkmcnt(0)
	ds_read2_b32 v[48:49], v31 offset1:16
	ds_read2_b32 v[50:51], v31 offset0:33 offset1:49
	ds_read2_b32 v[52:53], v31 offset0:66 offset1:82
	ds_read2_b32 v[54:55], v31 offset0:99 offset1:115
	ds_read2_b32 v[56:57], v31 offset0:132 offset1:148
	ds_read2_b32 v[58:59], v31 offset0:165 offset1:181
	ds_read2_b32 v[60:61], v31 offset0:198 offset1:214
	ds_read2_b32 v[62:63], v31 offset0:231 offset1:247
	ds_read2_b32 v[64:65], v41 offset0:8 offset1:24
	ds_read2_b32 v[66:67], v41 offset0:41 offset1:57
	ds_read2_b32 v[68:69], v41 offset0:74 offset1:90
	ds_read2_b32 v[70:71], v41 offset0:107 offset1:123
	ds_read2_b32 v[72:73], v41 offset0:140 offset1:156
	ds_read2_b32 v[74:75], v41 offset0:173 offset1:189
	ds_read2_b32 v[76:77], v41 offset0:206 offset1:222
	ds_read2_b32 v[78:79], v41 offset0:239 offset1:255
	s_addc_u32 s5, s9, 0
	v_mov_b32_e32 v42, v15
	v_mov_b32_e32 v43, v15
	v_mov_b32_e32 v44, v15
	v_mov_b32_e32 v45, v15
	v_lshl_add_u64 v[46:47], s[4:5], 0, v[2:3]
	s_waitcnt lgkmcnt(14)
	v_cvt_scalef32_pk_fp8_f32 v42, v48, v50, s46
	s_waitcnt lgkmcnt(10)
	v_cvt_scalef32_pk_fp8_f32 v43, v56, v58, s46
	s_waitcnt lgkmcnt(6)
	v_cvt_scalef32_pk_fp8_f32 v44, v64, v66, s46
	s_waitcnt lgkmcnt(2)
	v_cvt_scalef32_pk_fp8_f32 v45, v72, v74, s46
	v_cvt_scalef32_pk_fp8_f32 v42, v52, v54, s46 op_sel:[0,0,0,1]
	v_cvt_scalef32_pk_fp8_f32 v43, v60, v62, s46 op_sel:[0,0,0,1]
	v_cvt_scalef32_pk_fp8_f32 v44, v68, v70, s46 op_sel:[0,0,0,1]
	s_waitcnt lgkmcnt(0)
	v_cvt_scalef32_pk_fp8_f32 v45, v76, v78, s46 op_sel:[0,0,0,1]
	v_lshl_add_u64 v[80:81], v[46:47], 0, v[4:5]
	global_store_dwordx4 v[80:81], v[42:45], off sc1
	v_lshl_add_u64 v[46:47], v[46:47], 0, v[6:7]
	s_mov_b64 s[4:5], 0
	v_mov_b32_e32 v42, v15
	v_mov_b32_e32 v43, v15
	v_mov_b32_e32 v44, v15
	v_mov_b32_e32 v45, v15
	v_cvt_scalef32_pk_fp8_f32 v42, v49, v51, s46
	v_cvt_scalef32_pk_fp8_f32 v43, v57, v59, s46
	v_cvt_scalef32_pk_fp8_f32 v44, v65, v67, s46
	v_cvt_scalef32_pk_fp8_f32 v45, v73, v75, s46
	v_cvt_scalef32_pk_fp8_f32 v42, v53, v55, s46 op_sel:[0,0,0,1]
	v_cvt_scalef32_pk_fp8_f32 v43, v61, v63, s46 op_sel:[0,0,0,1]
	v_cvt_scalef32_pk_fp8_f32 v44, v69, v71, s46 op_sel:[0,0,0,1]
	v_cvt_scalef32_pk_fp8_f32 v45, v77, v79, s46 op_sel:[0,0,0,1]
	global_store_dwordx4 v[46:47], v[42:45], off sc1
	s_waitcnt lgkmcnt(0)
.LBB0_33:
	s_andn2_b64 vcc, exec, s[4:5]
	s_cbranch_vccnz .LBB0_35
	s_add_i32 s0, s68, 0xfffe8180
	s_lshr_b32 s0, s0, 7
	s_and_b32 s62, s33, 0x1e0
	s_lshl_b64 s[4:5], s[0:1], 20
	s_add_u32 s63, s22, s4
	s_addc_u32 s69, s23, s5
	s_lshl_b32 s0, s0, 9
	s_or_b32 s0, s0, s62
	s_and_b32 s8, s44, 0x1c0
	s_lshl_b64 s[4:5], s[0:1], 9
	v_readlane_b32 s0, v254, 9
	s_add_u32 s0, s0, s4
	v_readlane_b32 s4, v254, 10
	s_addc_u32 s9, s4, s5
	s_lshl_b32 s4, s8, 11
	s_add_u32 s4, s63, s4
	s_addc_u32 s5, s69, 0
	s_lshl_b32 s62, s62, 2
	s_add_u32 s4, s4, s62
	s_addc_u32 s5, s5, 0
	s_add_u32 s62, s4, 0x1000
	s_addc_u32 s63, s5, 0
	global_load_dword v19, v27, s[4:5] nt
	global_load_dword v21, v27, s[62:63] nt
	s_add_u32 s62, s4, 0x2000
	s_addc_u32 s63, s5, 0
	global_load_dword v23, v27, s[62:63] nt
	s_add_u32 s62, s4, 0x3000
	s_addc_u32 s63, s5, 0
	global_load_dword v25, v27, s[62:63] nt
	s_add_u32 s62, s4, 0x4000
	s_addc_u32 s63, s5, 0
	global_load_dword v42, v27, s[62:63] nt
	s_add_u32 s62, s4, 0x5000
	s_addc_u32 s63, s5, 0
	global_load_dword v43, v27, s[62:63] nt
	s_add_u32 s62, s4, 0x6000
	s_addc_u32 s63, s5, 0
	global_load_dword v44, v27, s[62:63] nt
	s_add_u32 s62, s4, 0x7000
	s_addc_u32 s63, s5, 0
	global_load_dword v45, v27, s[62:63] nt
	s_add_u32 s62, s4, 0x8000
	s_addc_u32 s63, s5, 0
	global_load_dword v46, v27, s[62:63] nt
	s_add_u32 s62, s4, 0x9000
	s_addc_u32 s63, s5, 0
	global_load_dword v47, v27, s[62:63] nt
	s_add_u32 s62, s4, 0xa000
	s_addc_u32 s63, s5, 0
	global_load_dword v48, v27, s[62:63] nt
	s_add_u32 s62, s4, 0xb000
	s_addc_u32 s63, s5, 0
	global_load_dword v49, v27, s[62:63] nt
	s_add_u32 s62, s4, 0xc000
	s_addc_u32 s63, s5, 0
	global_load_dword v50, v27, s[62:63] nt
	s_add_u32 s62, s4, 0xd000
	s_addc_u32 s63, s5, 0
	global_load_dword v51, v27, s[62:63] nt
	s_add_u32 s62, s4, 0xe000
	s_addc_u32 s63, s5, 0
	global_load_dword v52, v27, s[62:63] nt
	s_add_u32 s62, s4, 0xf000
	s_addc_u32 s63, s5, 0
	global_load_dword v53, v27, s[62:63] nt
	s_add_u32 s62, s4, 0x10000
	s_addc_u32 s63, s5, 0
	global_load_dword v54, v27, s[62:63] nt
	s_add_u32 s62, s4, 0x11000
	s_addc_u32 s63, s5, 0
	global_load_dword v55, v27, s[62:63] nt
	s_add_u32 s62, s4, 0x12000
	s_addc_u32 s63, s5, 0
	global_load_dword v56, v27, s[62:63] nt
	s_add_u32 s62, s4, 0x13000
	s_addc_u32 s63, s5, 0
	global_load_dword v57, v27, s[62:63] nt
	s_add_u32 s62, s4, 0x14000
	s_addc_u32 s63, s5, 0
	global_load_dword v58, v27, s[62:63] nt
	s_add_u32 s62, s4, 0x15000
	s_addc_u32 s63, s5, 0
	global_load_dword v59, v27, s[62:63] nt
	s_add_u32 s62, s4, 0x16000
	s_addc_u32 s63, s5, 0
	global_load_dword v60, v27, s[62:63] nt
	s_add_u32 s62, s4, 0x17000
	s_addc_u32 s63, s5, 0
	global_load_dword v61, v27, s[62:63] nt
	s_add_u32 s62, s4, 0x18000
	s_addc_u32 s63, s5, 0
	global_load_dword v62, v27, s[62:63] nt
	s_add_u32 s62, s4, 0x19000
	s_addc_u32 s63, s5, 0
	global_load_dword v63, v27, s[62:63] nt
	s_add_u32 s62, s4, 0x1a000
	s_addc_u32 s63, s5, 0
	global_load_dword v64, v27, s[62:63] nt
	s_add_u32 s62, s4, 0x1b000
	s_addc_u32 s63, s5, 0
	global_load_dword v65, v27, s[62:63] nt
	s_add_u32 s62, s4, 0x1c000
	s_addc_u32 s63, s5, 0
	global_load_dword v66, v27, s[62:63] nt
	s_add_u32 s62, s4, 0x1d000
	s_addc_u32 s63, s5, 0
	global_load_dword v67, v27, s[62:63] nt
	s_add_u32 s62, s4, 0x1e000
	s_addc_u32 s63, s5, 0
	s_add_u32 s4, s4, 0x1f000
	global_load_dword v68, v27, s[62:63] nt
	s_addc_u32 s5, s5, 0
	global_load_dword v69, v27, s[4:5] nt
	s_waitcnt vmcnt(0)
	s_add_u32 s4, s0, s8
	ds_write2_b32 v30, v19, v21 offset1:66
	ds_write2_b32 v30, v23, v25 offset0:132 offset1:198
	ds_write2_b32 v34, v42, v43 offset0:8 offset1:74
	ds_write2_b32 v34, v44, v45 offset0:140 offset1:206
	ds_write2_b32 v35, v46, v47 offset0:16 offset1:82
	ds_write2_b32 v35, v48, v49 offset0:148 offset1:214
	ds_write2_b32 v36, v50, v51 offset0:24 offset1:90
	ds_write2_b32 v36, v52, v53 offset0:156 offset1:222
	ds_write2_b32 v37, v54, v55 offset0:32 offset1:98
	ds_write2_b32 v37, v56, v57 offset0:164 offset1:230
	ds_write2_b32 v38, v58, v59 offset0:40 offset1:106
	ds_write2_b32 v38, v60, v61 offset0:172 offset1:238
	ds_write2_b32 v39, v62, v63 offset0:48 offset1:114
	ds_write2_b32 v39, v64, v65 offset0:180 offset1:246
	ds_write2_b32 v40, v66, v67 offset0:56 offset1:122
	ds_write2_b32 v40, v68, v69 offset0:188 offset1:254
	s_waitcnt lgkmcnt(0)
	ds_read2_b32 v[48:49], v31 offset1:16
	ds_read2_b32 v[50:51], v31 offset0:33 offset1:49
	ds_read2_b32 v[52:53], v31 offset0:66 offset1:82
	ds_read2_b32 v[54:55], v31 offset0:99 offset1:115
	ds_read2_b32 v[56:57], v31 offset0:132 offset1:148
	ds_read2_b32 v[58:59], v31 offset0:165 offset1:181
	ds_read2_b32 v[60:61], v31 offset0:198 offset1:214
	ds_read2_b32 v[62:63], v31 offset0:231 offset1:247
	ds_read2_b32 v[64:65], v41 offset0:8 offset1:24
	ds_read2_b32 v[66:67], v41 offset0:41 offset1:57
	ds_read2_b32 v[68:69], v41 offset0:74 offset1:90
	ds_read2_b32 v[70:71], v41 offset0:107 offset1:123
	ds_read2_b32 v[72:73], v41 offset0:140 offset1:156
	ds_read2_b32 v[74:75], v41 offset0:173 offset1:189
	ds_read2_b32 v[76:77], v41 offset0:206 offset1:222
	ds_read2_b32 v[78:79], v41 offset0:239 offset1:255
	s_addc_u32 s5, s9, 0
	v_mov_b32_e32 v42, v15
	v_mov_b32_e32 v43, v15
	v_mov_b32_e32 v44, v15
	v_mov_b32_e32 v45, v15
	v_lshl_add_u64 v[46:47], s[4:5], 0, v[2:3]
	s_waitcnt lgkmcnt(14)
	v_cvt_scalef32_pk_fp8_f32 v42, v48, v50, s47
	s_waitcnt lgkmcnt(10)
	v_cvt_scalef32_pk_fp8_f32 v43, v56, v58, s47
	s_waitcnt lgkmcnt(6)
	v_cvt_scalef32_pk_fp8_f32 v44, v64, v66, s47
	s_waitcnt lgkmcnt(2)
	v_cvt_scalef32_pk_fp8_f32 v45, v72, v74, s47
	v_cvt_scalef32_pk_fp8_f32 v42, v52, v54, s47 op_sel:[0,0,0,1]
	v_cvt_scalef32_pk_fp8_f32 v43, v60, v62, s47 op_sel:[0,0,0,1]
	v_cvt_scalef32_pk_fp8_f32 v44, v68, v70, s47 op_sel:[0,0,0,1]
	s_waitcnt lgkmcnt(0)
	v_cvt_scalef32_pk_fp8_f32 v45, v76, v78, s47 op_sel:[0,0,0,1]
	v_lshl_add_u64 v[80:81], v[46:47], 0, v[8:9]
	global_store_dwordx4 v[80:81], v[42:45], off sc1
	v_lshl_add_u64 v[46:47], v[46:47], 0, v[10:11]
	s_nop 0
	v_mov_b32_e32 v42, v15
	v_mov_b32_e32 v43, v15
	v_mov_b32_e32 v44, v15
	v_mov_b32_e32 v45, v15
	v_cvt_scalef32_pk_fp8_f32 v42, v49, v51, s47
	v_cvt_scalef32_pk_fp8_f32 v43, v57, v59, s47
	v_cvt_scalef32_pk_fp8_f32 v44, v65, v67, s47
	v_cvt_scalef32_pk_fp8_f32 v45, v73, v75, s47
	v_cvt_scalef32_pk_fp8_f32 v42, v53, v55, s47 op_sel:[0,0,0,1]
	v_cvt_scalef32_pk_fp8_f32 v43, v61, v63, s47 op_sel:[0,0,0,1]
	v_cvt_scalef32_pk_fp8_f32 v44, v69, v71, s47 op_sel:[0,0,0,1]
	v_cvt_scalef32_pk_fp8_f32 v45, v77, v79, s47 op_sel:[0,0,0,1]
	global_store_dwordx4 v[46:47], v[42:45], off sc1
	s_waitcnt lgkmcnt(0)

.LBB0_36:
	s_andn2_b64 vcc, exec, s[4:5]
	s_cbranch_vccnz .LBB0_38
	s_add_i32 s0, s68, 0xfffe8580
	s_and_b32 s62, s33, 0xfe0
	s_lshr_b32 s0, s0, 1
	s_and_b32 s0, s0, 0x7fffffc0
	s_lshl_b32 s4, s62, 9
	v_readlane_b32 s5, v254, 7
	s_add_u32 s8, s5, s4
	v_readlane_b32 s4, v254, 8
	s_addc_u32 s9, s4, 0
	s_lshl_b64 s[4:5], s[0:1], 14
	s_add_u32 s4, s20, s4
	s_addc_u32 s5, s21, s5
	s_lshl_b32 s62, s62, 2
	s_add_u32 s4, s4, s62
	s_addc_u32 s5, s5, 0
	s_add_u32 s62, s4, 0x8000
	s_addc_u32 s63, s5, 0
	global_load_dword v19, v26, s[4:5] nt
	global_load_dword v21, v26, s[62:63] nt
	s_add_u32 s62, s4, 0x10000
	s_addc_u32 s63, s5, 0
	global_load_dword v23, v26, s[62:63] nt
	s_add_u32 s62, s4, 0x18000
	s_addc_u32 s63, s5, 0
	global_load_dword v25, v26, s[62:63] nt
	s_add_u32 s62, s4, 0x20000
	s_addc_u32 s63, s5, 0
	global_load_dword v42, v26, s[62:63] nt
	s_add_u32 s62, s4, 0x28000
	s_addc_u32 s63, s5, 0
	global_load_dword v43, v26, s[62:63] nt
	s_add_u32 s62, s4, 0x30000
	s_addc_u32 s63, s5, 0
	global_load_dword v44, v26, s[62:63] nt
	s_add_u32 s62, s4, 0x38000
	s_addc_u32 s63, s5, 0
	global_load_dword v45, v26, s[62:63] nt
	s_add_u32 s62, s4, 0x40000
	s_addc_u32 s63, s5, 0
	global_load_dword v46, v26, s[62:63] nt
	s_add_u32 s62, s4, 0x48000
	s_addc_u32 s63, s5, 0
	global_load_dword v47, v26, s[62:63] nt
	s_add_u32 s62, s4, 0x50000
	s_addc_u32 s63, s5, 0
	global_load_dword v48, v26, s[62:63] nt
	s_add_u32 s62, s4, 0x58000
	s_addc_u32 s63, s5, 0
	global_load_dword v49, v26, s[62:63] nt
	s_add_u32 s62, s4, 0x60000
	s_addc_u32 s63, s5, 0
	global_load_dword v50, v26, s[62:63] nt
	s_add_u32 s62, s4, 0x68000
	s_addc_u32 s63, s5, 0
	global_load_dword v51, v26, s[62:63] nt
	s_add_u32 s62, s4, 0x70000
	s_addc_u32 s63, s5, 0
	global_load_dword v52, v26, s[62:63] nt
	s_add_u32 s62, s4, 0x78000
	s_addc_u32 s63, s5, 0
	global_load_dword v53, v26, s[62:63] nt
	s_add_u32 s62, s4, 0x80000
	s_addc_u32 s63, s5, 0
	global_load_dword v54, v26, s[62:63] nt
	s_add_u32 s62, s4, 0x88000
	s_addc_u32 s63, s5, 0
	global_load_dword v55, v26, s[62:63] nt
	s_add_u32 s62, s4, 0x90000
	s_addc_u32 s63, s5, 0
	global_load_dword v56, v26, s[62:63] nt
	s_add_u32 s62, s4, 0x98000
	s_addc_u32 s63, s5, 0
	global_load_dword v57, v26, s[62:63] nt
	s_add_u32 s62, s4, 0xa0000
	s_addc_u32 s63, s5, 0
	global_load_dword v58, v26, s[62:63] nt
	s_add_u32 s62, s4, 0xa8000
	s_addc_u32 s63, s5, 0
	global_load_dword v59, v26, s[62:63] nt
	s_add_u32 s62, s4, 0xb0000
	s_addc_u32 s63, s5, 0
	global_load_dword v60, v26, s[62:63] nt
	s_add_u32 s62, s4, 0xb8000
	s_addc_u32 s63, s5, 0
	global_load_dword v61, v26, s[62:63] nt
	s_add_u32 s62, s4, 0xc0000
	s_addc_u32 s63, s5, 0
	global_load_dword v62, v26, s[62:63] nt
	s_add_u32 s62, s4, 0xc8000
	s_addc_u32 s63, s5, 0
	global_load_dword v63, v26, s[62:63] nt
	s_add_u32 s62, s4, 0xd0000
	s_addc_u32 s63, s5, 0
	global_load_dword v64, v26, s[62:63] nt
	s_add_u32 s62, s4, 0xd8000
	s_addc_u32 s63, s5, 0
	global_load_dword v65, v26, s[62:63] nt
	s_add_u32 s62, s4, 0xe0000
	s_addc_u32 s63, s5, 0
	global_load_dword v66, v26, s[62:63] nt
	s_add_u32 s62, s4, 0xe8000
	s_addc_u32 s63, s5, 0
	global_load_dword v67, v26, s[62:63] nt
	s_add_u32 s62, s4, 0xf0000
	s_addc_u32 s63, s5, 0
	s_add_u32 s4, s4, 0xf8000
	global_load_dword v68, v26, s[62:63] nt
	s_addc_u32 s5, s5, 0
	global_load_dword v69, v26, s[4:5] nt
	s_waitcnt vmcnt(0)
	s_add_u32 s4, s8, s0
	ds_write2_b32 v30, v19, v21 offset1:66
	ds_write2_b32 v30, v23, v25 offset0:132 offset1:198
	ds_write2_b32 v34, v42, v43 offset0:8 offset1:74
	ds_write2_b32 v34, v44, v45 offset0:140 offset1:206
	ds_write2_b32 v35, v46, v47 offset0:16 offset1:82
	ds_write2_b32 v35, v48, v49 offset0:148 offset1:214
	ds_write2_b32 v36, v50, v51 offset0:24 offset1:90
	ds_write2_b32 v36, v52, v53 offset0:156 offset1:222
	ds_write2_b32 v37, v54, v55 offset0:32 offset1:98
	ds_write2_b32 v37, v56, v57 offset0:164 offset1:230
	ds_write2_b32 v38, v58, v59 offset0:40 offset1:106
	ds_write2_b32 v38, v60, v61 offset0:172 offset1:238
	ds_write2_b32 v39, v62, v63 offset0:48 offset1:114
	ds_write2_b32 v39, v64, v65 offset0:180 offset1:246
	ds_write2_b32 v40, v66, v67 offset0:56 offset1:122
	ds_write2_b32 v40, v68, v69 offset0:188 offset1:254
	s_waitcnt lgkmcnt(0)
	ds_read2_b32 v[48:49], v31 offset1:16
	ds_read2_b32 v[50:51], v31 offset0:33 offset1:49
	ds_read2_b32 v[52:53], v31 offset0:66 offset1:82
	ds_read2_b32 v[54:55], v31 offset0:99 offset1:115
	ds_read2_b32 v[56:57], v31 offset0:132 offset1:148
	ds_read2_b32 v[58:59], v31 offset0:165 offset1:181
	ds_read2_b32 v[60:61], v31 offset0:198 offset1:214
	ds_read2_b32 v[62:63], v31 offset0:231 offset1:247
	ds_read2_b32 v[64:65], v41 offset0:8 offset1:24
	ds_read2_b32 v[66:67], v41 offset0:41 offset1:57
	ds_read2_b32 v[68:69], v41 offset0:74 offset1:90
	ds_read2_b32 v[70:71], v41 offset0:107 offset1:123
	ds_read2_b32 v[72:73], v41 offset0:140 offset1:156
	ds_read2_b32 v[74:75], v41 offset0:173 offset1:189
	ds_read2_b32 v[76:77], v41 offset0:206 offset1:222
	ds_read2_b32 v[78:79], v41 offset0:239 offset1:255
	s_addc_u32 s5, s9, 0
	v_mov_b32_e32 v42, v15
	v_mov_b32_e32 v43, v15
	v_mov_b32_e32 v44, v15
	v_mov_b32_e32 v45, v15
	v_lshl_add_u64 v[46:47], s[4:5], 0, v[2:3]
	s_waitcnt lgkmcnt(14)
	v_cvt_scalef32_pk_fp8_f32 v42, v48, v50, s47
	s_waitcnt lgkmcnt(10)
	v_cvt_scalef32_pk_fp8_f32 v43, v56, v58, s47
	s_waitcnt lgkmcnt(6)
	v_cvt_scalef32_pk_fp8_f32 v44, v64, v66, s47
	s_waitcnt lgkmcnt(2)
	v_cvt_scalef32_pk_fp8_f32 v45, v72, v74, s47
	v_cvt_scalef32_pk_fp8_f32 v42, v52, v54, s47 op_sel:[0,0,0,1]
	v_cvt_scalef32_pk_fp8_f32 v43, v60, v62, s47 op_sel:[0,0,0,1]
	v_cvt_scalef32_pk_fp8_f32 v44, v68, v70, s47 op_sel:[0,0,0,1]
	s_waitcnt lgkmcnt(0)
	v_cvt_scalef32_pk_fp8_f32 v45, v76, v78, s47 op_sel:[0,0,0,1]
	v_lshl_add_u64 v[80:81], v[46:47], 0, v[8:9]
	global_store_dwordx4 v[80:81], v[42:45], off sc1
	v_lshl_add_u64 v[46:47], v[46:47], 0, v[10:11]
	s_nop 0
	v_mov_b32_e32 v42, v15
	v_mov_b32_e32 v43, v15
	v_mov_b32_e32 v44, v15
	v_mov_b32_e32 v45, v15
	v_cvt_scalef32_pk_fp8_f32 v42, v49, v51, s47
	v_cvt_scalef32_pk_fp8_f32 v43, v57, v59, s47
	v_cvt_scalef32_pk_fp8_f32 v44, v65, v67, s47
	v_cvt_scalef32_pk_fp8_f32 v45, v73, v75, s47
	v_cvt_scalef32_pk_fp8_f32 v42, v53, v55, s47 op_sel:[0,0,0,1]
	v_cvt_scalef32_pk_fp8_f32 v43, v61, v63, s47 op_sel:[0,0,0,1]
	v_cvt_scalef32_pk_fp8_f32 v44, v69, v71, s47 op_sel:[0,0,0,1]
	v_cvt_scalef32_pk_fp8_f32 v45, v77, v79, s47 op_sel:[0,0,0,1]
	global_store_dwordx4 v[46:47], v[42:45], off sc1
	s_waitcnt lgkmcnt(0)

.LBB0_39:
	s_andn2_b64 vcc, exec, s[4:5]
	s_cbranch_vccnz .LBB0_41
	s_add_i32 s0, s68, 0x8b80
	s_and_b32 s4, s0, 0xffff
	s_mul_i32 s4, s4, 0xaaab
	s_lshr_b32 s5, s4, 16
	s_lshr_b32 s4, s4, 22
	s_mulk_i32 s4, 0x60
	s_sub_i32 s0, s0, s4
	s_and_b32 s4, s0, 0xffff
	s_lshl_b32 s0, s4, 15
	v_readlane_b32 s8, v254, 5
	s_add_u32 s0, s8, s0
	v_readlane_b32 s8, v254, 6
	s_addc_u32 s8, s8, 0
	s_and_b32 s9, s5, 0xffc0
	s_mul_i32 s5, s9, 0x3000
	s_add_u32 s5, s16, s5
	s_addc_u32 s62, s17, 0
	s_lshl_b32 s4, s4, 7
	s_add_u32 s4, s5, s4
	s_addc_u32 s5, s62, 0
	s_add_u32 s62, s4, 0x6000
	s_addc_u32 s63, s5, 0
	global_load_dword v19, v28, s[4:5] nt
	global_load_dword v21, v28, s[62:63] nt
	s_add_u32 s62, s4, 0xc000
	s_addc_u32 s63, s5, 0
	global_load_dword v23, v28, s[62:63] nt
	s_add_u32 s62, s4, 0x12000
	s_addc_u32 s63, s5, 0
	global_load_dword v25, v28, s[62:63] nt
	s_add_u32 s62, s4, 0x18000
	s_addc_u32 s63, s5, 0
	global_load_dword v42, v28, s[62:63] nt
	s_add_u32 s62, s4, 0x1e000
	s_addc_u32 s63, s5, 0
	global_load_dword v43, v28, s[62:63] nt
	s_add_u32 s62, s4, 0x24000
	s_addc_u32 s63, s5, 0
	global_load_dword v44, v28, s[62:63] nt
	s_add_u32 s62, s4, 0x2a000
	s_addc_u32 s63, s5, 0
	global_load_dword v45, v28, s[62:63] nt
	s_add_u32 s62, s4, 0x30000
	s_addc_u32 s63, s5, 0
	global_load_dword v46, v28, s[62:63] nt
	s_add_u32 s62, s4, 0x36000
	s_addc_u32 s63, s5, 0
	global_load_dword v47, v28, s[62:63] nt
	s_add_u32 s62, s4, 0x3c000
	s_addc_u32 s63, s5, 0
	global_load_dword v48, v28, s[62:63] nt
	s_add_u32 s62, s4, 0x42000
	s_addc_u32 s63, s5, 0
	global_load_dword v49, v28, s[62:63] nt
	s_add_u32 s62, s4, 0x48000
	s_addc_u32 s63, s5, 0
	global_load_dword v50, v28, s[62:63] nt
	s_add_u32 s62, s4, 0x4e000
	s_addc_u32 s63, s5, 0
	global_load_dword v51, v28, s[62:63] nt
	s_add_u32 s62, s4, 0x54000
	s_addc_u32 s63, s5, 0
	global_load_dword v52, v28, s[62:63] nt
	s_add_u32 s62, s4, 0x5a000
	s_addc_u32 s63, s5, 0
	global_load_dword v53, v28, s[62:63] nt
	s_add_u32 s62, s4, 0x60000
	s_addc_u32 s63, s5, 0
	global_load_dword v54, v28, s[62:63] nt
	s_add_u32 s62, s4, 0x66000
	s_addc_u32 s63, s5, 0
	global_load_dword v55, v28, s[62:63] nt
	s_add_u32 s62, s4, 0x6c000
	s_addc_u32 s63, s5, 0
	global_load_dword v56, v28, s[62:63] nt
	s_add_u32 s62, s4, 0x72000
	s_addc_u32 s63, s5, 0
	global_load_dword v57, v28, s[62:63] nt
	s_add_u32 s62, s4, 0x78000
	s_addc_u32 s63, s5, 0
	global_load_dword v58, v28, s[62:63] nt
	s_add_u32 s62, s4, 0x7e000
	s_addc_u32 s63, s5, 0
	global_load_dword v59, v28, s[62:63] nt
	s_add_u32 s62, s4, 0x84000
	s_addc_u32 s63, s5, 0
	global_load_dword v60, v28, s[62:63] nt
	s_add_u32 s62, s4, 0x8a000
	s_addc_u32 s63, s5, 0
	global_load_dword v61, v28, s[62:63] nt
	s_add_u32 s62, s4, 0x90000
	s_addc_u32 s63, s5, 0
	global_load_dword v62, v28, s[62:63] nt
	s_add_u32 s62, s4, 0x96000
	s_addc_u32 s63, s5, 0
	global_load_dword v63, v28, s[62:63] nt
	s_add_u32 s62, s4, 0x9c000
	s_addc_u32 s63, s5, 0
	global_load_dword v64, v28, s[62:63] nt
	s_add_u32 s62, s4, 0xa2000
	s_addc_u32 s63, s5, 0
	global_load_dword v65, v28, s[62:63] nt
	s_add_u32 s62, s4, 0xa8000
	s_addc_u32 s63, s5, 0
	global_load_dword v66, v28, s[62:63] nt
	s_add_u32 s62, s4, 0xae000
	s_addc_u32 s63, s5, 0
	global_load_dword v67, v28, s[62:63] nt
	s_add_u32 s62, s4, 0xb4000
	s_addc_u32 s63, s5, 0
	s_add_u32 s4, s4, 0xba000
	global_load_dword v68, v28, s[62:63] nt
	s_addc_u32 s5, s5, 0
	global_load_dword v69, v28, s[4:5] nt
	s_waitcnt vmcnt(0)
	s_add_u32 s4, s0, s9
	ds_write2_b32 v30, v19, v21 offset1:66
	ds_write2_b32 v30, v23, v25 offset0:132 offset1:198
	ds_write2_b32 v34, v42, v43 offset0:8 offset1:74
	ds_write2_b32 v34, v44, v45 offset0:140 offset1:206
	ds_write2_b32 v35, v46, v47 offset0:16 offset1:82
	ds_write2_b32 v35, v48, v49 offset0:148 offset1:214
	ds_write2_b32 v36, v50, v51 offset0:24 offset1:90
	ds_write2_b32 v36, v52, v53 offset0:156 offset1:222
	ds_write2_b32 v37, v54, v55 offset0:32 offset1:98
	ds_write2_b32 v37, v56, v57 offset0:164 offset1:230
	ds_write2_b32 v38, v58, v59 offset0:40 offset1:106
	ds_write2_b32 v38, v60, v61 offset0:172 offset1:238
	ds_write2_b32 v39, v62, v63 offset0:48 offset1:114
	ds_write2_b32 v39, v64, v65 offset0:180 offset1:246
	ds_write2_b32 v40, v66, v67 offset0:56 offset1:122
	ds_write2_b32 v40, v68, v69 offset0:188 offset1:254
	s_waitcnt lgkmcnt(0)
	ds_read2_b32 v[48:49], v31 offset1:16
	ds_read2_b32 v[50:51], v31 offset0:33 offset1:49
	ds_read2_b32 v[52:53], v31 offset0:66 offset1:82
	ds_read2_b32 v[54:55], v31 offset0:99 offset1:115
	ds_read2_b32 v[56:57], v31 offset0:132 offset1:148
	ds_read2_b32 v[58:59], v31 offset0:165 offset1:181
	ds_read2_b32 v[60:61], v31 offset0:198 offset1:214
	ds_read2_b32 v[62:63], v31 offset0:231 offset1:247
	ds_read2_b32 v[64:65], v41 offset0:8 offset1:24
	ds_read2_b32 v[66:67], v41 offset0:41 offset1:57
	ds_read2_b32 v[68:69], v41 offset0:74 offset1:90
	ds_read2_b32 v[70:71], v41 offset0:107 offset1:123
	ds_read2_b32 v[72:73], v41 offset0:140 offset1:156
	ds_read2_b32 v[74:75], v41 offset0:173 offset1:189
	ds_read2_b32 v[76:77], v41 offset0:206 offset1:222
	ds_read2_b32 v[78:79], v41 offset0:239 offset1:255
	s_addc_u32 s5, s8, 0
	v_mov_b32_e32 v42, v15
	v_mov_b32_e32 v43, v15
	v_mov_b32_e32 v44, v15
	v_mov_b32_e32 v45, v15
	v_lshl_add_u64 v[46:47], s[4:5], 0, v[2:3]
	s_waitcnt lgkmcnt(14)
	v_cvt_scalef32_pk_fp8_f32 v42, v48, v50, s48
	s_waitcnt lgkmcnt(10)
	v_cvt_scalef32_pk_fp8_f32 v43, v56, v58, s48
	s_waitcnt lgkmcnt(6)
	v_cvt_scalef32_pk_fp8_f32 v44, v64, v66, s48
	s_waitcnt lgkmcnt(2)
	v_cvt_scalef32_pk_fp8_f32 v45, v72, v74, s48
	v_cvt_scalef32_pk_fp8_f32 v42, v52, v54, s48 op_sel:[0,0,0,1]
	v_cvt_scalef32_pk_fp8_f32 v43, v60, v62, s48 op_sel:[0,0,0,1]
	v_cvt_scalef32_pk_fp8_f32 v44, v68, v70, s48 op_sel:[0,0,0,1]
	s_waitcnt lgkmcnt(0)
	v_cvt_scalef32_pk_fp8_f32 v45, v76, v78, s48 op_sel:[0,0,0,1]
	v_lshl_add_u64 v[80:81], v[46:47], 0, v[12:13]
	global_store_dwordx4 v[80:81], v[42:45], off sc1
	v_lshl_add_u64 v[46:47], v[46:47], 0, v[16:17]
	s_nop 0
	v_mov_b32_e32 v42, v15
	v_mov_b32_e32 v43, v15
	v_mov_b32_e32 v44, v15
	v_mov_b32_e32 v45, v15
	v_cvt_scalef32_pk_fp8_f32 v42, v49, v51, s48
	v_cvt_scalef32_pk_fp8_f32 v43, v57, v59, s48
	v_cvt_scalef32_pk_fp8_f32 v44, v65, v67, s48
	v_cvt_scalef32_pk_fp8_f32 v45, v73, v75, s48
	v_cvt_scalef32_pk_fp8_f32 v42, v53, v55, s48 op_sel:[0,0,0,1]
	v_cvt_scalef32_pk_fp8_f32 v43, v61, v63, s48 op_sel:[0,0,0,1]
	v_cvt_scalef32_pk_fp8_f32 v44, v69, v71, s48 op_sel:[0,0,0,1]
	v_cvt_scalef32_pk_fp8_f32 v45, v77, v79, s48 op_sel:[0,0,0,1]
	global_store_dwordx4 v[46:47], v[42:45], off sc1
	s_waitcnt lgkmcnt(0)

.LBB0_42:
	s_andn2_b64 vcc, exec, s[4:5]
	s_cbranch_vccnz .LBB0_47
	s_add_i32 s0, s68, 0xa800
	s_bfe_u32 s4, s0, 0xf0001
	s_mul_i32 s4, s4, 0x8fb9
	s_lshr_b32 s8, s4, 21
	s_mul_i32 s4, s8, 0x72
	s_sub_i32 s0, s0, s4
	s_and_b32 s62, s0, 0xffff
	s_add_i32 s0, s0, 0xffe0
	s_lshl_b32 s9, s62, 5
	s_and_b32 s4, s0, 0xffff
	s_lshl_b32 s0, s8, 6
	s_cmp_gt_u32 s4, 17
	s_mov_b64 s[4:5], -1
	s_cbranch_scc0 .LBB0_45
	s_add_i32 s4, s9, 0xfffffdc0
	s_cmp_lt_u32 s62, 32
	s_cselect_b32 s4, s9, s4
	s_ashr_i32 s5, s4, 31
	s_lshl_b64 s[4:5], s[4:5], 12
	s_add_u32 s63, s6, s4
	s_addc_u32 s69, s7, s5
	s_mul_i32 s4, s0, 0x3900
	s_add_u32 s4, s12, s4
	s_addc_u32 s5, s13, 0
	s_lshl_b32 s70, s9, 2
	s_add_u32 s4, s4, s70
	s_addc_u32 s5, s5, 0
	s_add_u32 s70, s4, 0x7200
	s_addc_u32 s71, s5, 0
	global_load_dword v19, v29, s[4:5] nt
	global_load_dword v21, v29, s[70:71] nt
	s_add_u32 s70, s4, 0xe400
	s_addc_u32 s71, s5, 0
	global_load_dword v23, v29, s[70:71] nt
	s_add_u32 s70, s4, 0x15600
	s_addc_u32 s71, s5, 0
	global_load_dword v25, v29, s[70:71] nt
	s_add_u32 s70, s4, 0x1c800
	s_addc_u32 s71, s5, 0
	global_load_dword v42, v29, s[70:71] nt
	s_add_u32 s70, s4, 0x23a00
	s_addc_u32 s71, s5, 0
	global_load_dword v43, v29, s[70:71] nt
	s_add_u32 s70, s4, 0x2ac00
	s_addc_u32 s71, s5, 0
	global_load_dword v44, v29, s[70:71] nt
	s_add_u32 s70, s4, 0x31e00
	s_addc_u32 s71, s5, 0
	global_load_dword v45, v29, s[70:71] nt
	s_add_u32 s70, s4, 0x39000
	s_addc_u32 s71, s5, 0
	global_load_dword v46, v29, s[70:71] nt
	s_add_u32 s70, s4, 0x40200
	s_addc_u32 s71, s5, 0
	global_load_dword v47, v29, s[70:71] nt
	s_add_u32 s70, s4, 0x47400
	s_addc_u32 s71, s5, 0
	global_load_dword v48, v29, s[70:71] nt
	s_add_u32 s70, s4, 0x4e600
	s_addc_u32 s71, s5, 0
	global_load_dword v49, v29, s[70:71] nt
	s_add_u32 s70, s4, 0x55800
	s_addc_u32 s71, s5, 0
	global_load_dword v50, v29, s[70:71] nt
	s_add_u32 s70, s4, 0x5ca00
	s_addc_u32 s71, s5, 0
	global_load_dword v51, v29, s[70:71] nt
	s_add_u32 s70, s4, 0x63c00
	s_addc_u32 s71, s5, 0
	global_load_dword v52, v29, s[70:71] nt
	s_add_u32 s70, s4, 0x6ae00
	s_addc_u32 s71, s5, 0
	global_load_dword v53, v29, s[70:71] nt
	s_add_u32 s70, s4, 0x72000
	s_addc_u32 s71, s5, 0
	global_load_dword v54, v29, s[70:71] nt
	s_add_u32 s70, s4, 0x79200
	s_addc_u32 s71, s5, 0
	global_load_dword v55, v29, s[70:71] nt
	s_add_u32 s70, s4, 0x80400
	s_addc_u32 s71, s5, 0
	global_load_dword v56, v29, s[70:71] nt
	s_add_u32 s70, s4, 0x87600
	s_addc_u32 s71, s5, 0
	global_load_dword v57, v29, s[70:71] nt
	s_add_u32 s70, s4, 0x8e800
	s_addc_u32 s71, s5, 0
	global_load_dword v58, v29, s[70:71] nt
	s_add_u32 s70, s4, 0x95a00
	s_addc_u32 s71, s5, 0
	global_load_dword v59, v29, s[70:71] nt
	s_add_u32 s70, s4, 0x9cc00
	s_addc_u32 s71, s5, 0
	global_load_dword v60, v29, s[70:71] nt
	s_add_u32 s70, s4, 0xa3e00
	s_addc_u32 s71, s5, 0
	global_load_dword v61, v29, s[70:71] nt
	s_add_u32 s70, s4, 0xab000
	s_addc_u32 s71, s5, 0
	global_load_dword v62, v29, s[70:71] nt
	s_add_u32 s70, s4, 0xb2200
	s_addc_u32 s71, s5, 0
	global_load_dword v63, v29, s[70:71] nt
	s_add_u32 s70, s4, 0xb9400
	s_addc_u32 s71, s5, 0
	global_load_dword v64, v29, s[70:71] nt
	s_add_u32 s70, s4, 0xc0600
	s_addc_u32 s71, s5, 0
	global_load_dword v65, v29, s[70:71] nt
	s_add_u32 s70, s4, 0xc7800
	s_addc_u32 s71, s5, 0
	global_load_dword v66, v29, s[70:71] nt
	s_add_u32 s70, s4, 0xcea00
	s_addc_u32 s71, s5, 0
	global_load_dword v67, v29, s[70:71] nt
	s_add_u32 s70, s4, 0xd5c00
	s_addc_u32 s71, s5, 0
	s_add_u32 s4, s4, 0xdce00
	global_load_dword v68, v29, s[70:71] nt
	s_addc_u32 s5, s5, 0
	global_load_dword v69, v29, s[4:5] nt
	s_waitcnt vmcnt(0)
	s_add_u32 s4, s63, s0
	ds_write2_b32 v30, v19, v21 offset1:66
	ds_write2_b32 v30, v23, v25 offset0:132 offset1:198
	ds_write2_b32 v34, v42, v43 offset0:8 offset1:74
	ds_write2_b32 v34, v44, v45 offset0:140 offset1:206
	ds_write2_b32 v35, v46, v47 offset0:16 offset1:82
	ds_write2_b32 v35, v48, v49 offset0:148 offset1:214
	ds_write2_b32 v36, v50, v51 offset0:24 offset1:90
	ds_write2_b32 v36, v52, v53 offset0:156 offset1:222
	ds_write2_b32 v37, v54, v55 offset0:32 offset1:98
	ds_write2_b32 v37, v56, v57 offset0:164 offset1:230
	ds_write2_b32 v38, v58, v59 offset0:40 offset1:106
	ds_write2_b32 v38, v60, v61 offset0:172 offset1:238
	ds_write2_b32 v39, v62, v63 offset0:48 offset1:114
	ds_write2_b32 v39, v64, v65 offset0:180 offset1:246
	ds_write2_b32 v40, v66, v67 offset0:56 offset1:122
	ds_write2_b32 v40, v68, v69 offset0:188 offset1:254
	s_waitcnt lgkmcnt(0)
	ds_read2_b32 v[48:49], v31 offset1:16
	ds_read2_b32 v[50:51], v31 offset0:33 offset1:49
	ds_read2_b32 v[52:53], v31 offset0:66 offset1:82
	ds_read2_b32 v[54:55], v31 offset0:99 offset1:115
	ds_read2_b32 v[56:57], v31 offset0:132 offset1:148
	ds_read2_b32 v[58:59], v31 offset0:165 offset1:181
	ds_read2_b32 v[60:61], v31 offset0:198 offset1:214
	ds_read2_b32 v[62:63], v31 offset0:231 offset1:247
	ds_read2_b32 v[64:65], v41 offset0:8 offset1:24
	ds_read2_b32 v[66:67], v41 offset0:41 offset1:57
	ds_read2_b32 v[68:69], v41 offset0:74 offset1:90
	ds_read2_b32 v[70:71], v41 offset0:107 offset1:123
	ds_read2_b32 v[72:73], v41 offset0:140 offset1:156
	ds_read2_b32 v[74:75], v41 offset0:173 offset1:189
	ds_read2_b32 v[76:77], v41 offset0:206 offset1:222
	ds_read2_b32 v[78:79], v41 offset0:239 offset1:255
	s_addc_u32 s5, s69, 0
	v_mov_b32_e32 v42, v15
	v_mov_b32_e32 v43, v15
	v_mov_b32_e32 v44, v15
	v_mov_b32_e32 v45, v15
	v_lshl_add_u64 v[46:47], s[4:5], 0, v[2:3]
	s_waitcnt lgkmcnt(14)
	v_cvt_scalef32_pk_fp8_f32 v42, v48, v50, s49
	s_waitcnt lgkmcnt(10)
	v_cvt_scalef32_pk_fp8_f32 v43, v56, v58, s49
	s_waitcnt lgkmcnt(6)
	v_cvt_scalef32_pk_fp8_f32 v44, v64, v66, s49
	s_waitcnt lgkmcnt(2)
	v_cvt_scalef32_pk_fp8_f32 v45, v72, v74, s49
	v_cvt_scalef32_pk_fp8_f32 v42, v52, v54, s49 op_sel:[0,0,0,1]
	v_cvt_scalef32_pk_fp8_f32 v43, v60, v62, s49 op_sel:[0,0,0,1]
	v_cvt_scalef32_pk_fp8_f32 v44, v68, v70, s49 op_sel:[0,0,0,1]
	s_waitcnt lgkmcnt(0)
	v_cvt_scalef32_pk_fp8_f32 v45, v76, v78, s49 op_sel:[0,0,0,1]
	v_lshl_add_u64 v[80:81], v[46:47], 0, v[4:5]
	global_store_dwordx4 v[80:81], v[42:45], off sc1
	v_lshl_add_u64 v[46:47], v[46:47], 0, v[6:7]
	s_mov_b64 s[4:5], 0
	v_mov_b32_e32 v42, v15
	v_mov_b32_e32 v43, v15
	v_mov_b32_e32 v44, v15
	v_mov_b32_e32 v45, v15
	v_cvt_scalef32_pk_fp8_f32 v42, v49, v51, s49
	v_cvt_scalef32_pk_fp8_f32 v43, v57, v59, s49
	v_cvt_scalef32_pk_fp8_f32 v44, v65, v67, s49
	v_cvt_scalef32_pk_fp8_f32 v45, v73, v75, s49
	v_cvt_scalef32_pk_fp8_f32 v42, v53, v55, s49 op_sel:[0,0,0,1]
	v_cvt_scalef32_pk_fp8_f32 v43, v61, v63, s49 op_sel:[0,0,0,1]
	v_cvt_scalef32_pk_fp8_f32 v44, v69, v71, s49 op_sel:[0,0,0,1]
	v_cvt_scalef32_pk_fp8_f32 v45, v77, v79, s49 op_sel:[0,0,0,1]
	global_store_dwordx4 v[46:47], v[42:45], off sc1
	s_waitcnt lgkmcnt(0)
.LBB0_45:
	s_andn2_b64 vcc, exec, s[4:5]
	s_cbranch_vccnz .LBB0_47
	s_lshl_b32 s4, s62, 18
	s_add_u32 s63, s64, s4
	s_addc_u32 s62, s65, 0
	s_mul_i32 s8, s8, 0xe4000
	s_add_u32 s4, s12, s8
	s_addc_u32 s5, s13, 0
	s_lshl_b32 s8, s9, 2
	s_add_u32 s4, s4, s8
	s_addc_u32 s5, s5, 0
	s_add_u32 s8, s4, 0x7200
	s_addc_u32 s9, s5, 0
	global_load_dword v19, v29, s[4:5] nt
	global_load_dword v21, v29, s[8:9] nt
	s_add_u32 s8, s4, 0xe400
	s_addc_u32 s9, s5, 0
	global_load_dword v23, v29, s[8:9] nt
	s_add_u32 s8, s4, 0x15600
	s_addc_u32 s9, s5, 0
	global_load_dword v25, v29, s[8:9] nt
	s_add_u32 s8, s4, 0x1c800
	s_addc_u32 s9, s5, 0
	global_load_dword v42, v29, s[8:9] nt
	s_add_u32 s8, s4, 0x23a00
	s_addc_u32 s9, s5, 0
	global_load_dword v43, v29, s[8:9] nt
	s_add_u32 s8, s4, 0x2ac00
	s_addc_u32 s9, s5, 0
	global_load_dword v44, v29, s[8:9] nt
	s_add_u32 s8, s4, 0x31e00
	s_addc_u32 s9, s5, 0
	global_load_dword v45, v29, s[8:9] nt
	s_add_u32 s8, s4, 0x39000
	s_addc_u32 s9, s5, 0
	global_load_dword v46, v29, s[8:9] nt
	s_add_u32 s8, s4, 0x40200
	s_addc_u32 s9, s5, 0
	global_load_dword v47, v29, s[8:9] nt
	s_add_u32 s8, s4, 0x47400
	s_addc_u32 s9, s5, 0
	global_load_dword v48, v29, s[8:9] nt
	s_add_u32 s8, s4, 0x4e600
	s_addc_u32 s9, s5, 0
	global_load_dword v49, v29, s[8:9] nt
	s_add_u32 s8, s4, 0x55800
	s_addc_u32 s9, s5, 0
	global_load_dword v50, v29, s[8:9] nt
	s_add_u32 s8, s4, 0x5ca00
	s_addc_u32 s9, s5, 0
	global_load_dword v51, v29, s[8:9] nt
	s_add_u32 s8, s4, 0x63c00
	s_addc_u32 s9, s5, 0
	global_load_dword v52, v29, s[8:9] nt
	s_add_u32 s8, s4, 0x6ae00
	s_addc_u32 s9, s5, 0
	global_load_dword v53, v29, s[8:9] nt
	s_add_u32 s8, s4, 0x72000
	s_addc_u32 s9, s5, 0
	global_load_dword v54, v29, s[8:9] nt
	s_add_u32 s8, s4, 0x79200
	s_addc_u32 s9, s5, 0
	global_load_dword v55, v29, s[8:9] nt
	s_add_u32 s8, s4, 0x80400
	s_addc_u32 s9, s5, 0
	global_load_dword v56, v29, s[8:9] nt
	s_add_u32 s8, s4, 0x87600
	s_addc_u32 s9, s5, 0
	global_load_dword v57, v29, s[8:9] nt
	s_add_u32 s8, s4, 0x8e800
	s_addc_u32 s9, s5, 0
	global_load_dword v58, v29, s[8:9] nt
	s_add_u32 s8, s4, 0x95a00
	s_addc_u32 s9, s5, 0
	global_load_dword v59, v29, s[8:9] nt
	s_add_u32 s8, s4, 0x9cc00
	s_addc_u32 s9, s5, 0
	global_load_dword v60, v29, s[8:9] nt
	s_add_u32 s8, s4, 0xa3e00
	s_addc_u32 s9, s5, 0
	global_load_dword v61, v29, s[8:9] nt
	s_add_u32 s8, s4, 0xab000
	s_addc_u32 s9, s5, 0
	global_load_dword v62, v29, s[8:9] nt
	s_add_u32 s8, s4, 0xb2200
	s_addc_u32 s9, s5, 0
	global_load_dword v63, v29, s[8:9] nt
	s_add_u32 s8, s4, 0xb9400
	s_addc_u32 s9, s5, 0
	global_load_dword v64, v29, s[8:9] nt
	s_add_u32 s8, s4, 0xc0600
	s_addc_u32 s9, s5, 0
	global_load_dword v65, v29, s[8:9] nt
	s_add_u32 s8, s4, 0xc7800
	s_addc_u32 s9, s5, 0
	global_load_dword v66, v29, s[8:9] nt
	s_add_u32 s8, s4, 0xcea00
	s_addc_u32 s9, s5, 0
	global_load_dword v67, v29, s[8:9] nt
	s_add_u32 s8, s4, 0xd5c00
	s_addc_u32 s9, s5, 0
	s_add_u32 s4, s4, 0xdce00
	global_load_dword v68, v29, s[8:9] nt
	s_addc_u32 s5, s5, 0
	global_load_dword v69, v29, s[4:5] nt
	s_waitcnt vmcnt(0)
	s_lshl_b32 s0, s0, 1
	ds_write2_b32 v30, v19, v21 offset1:66
	ds_write2_b32 v30, v23, v25 offset0:132 offset1:198
	ds_write2_b32 v34, v42, v43 offset0:8 offset1:74
	ds_write2_b32 v34, v44, v45 offset0:140 offset1:206
	ds_write2_b32 v35, v46, v47 offset0:16 offset1:82
	ds_write2_b32 v35, v48, v49 offset0:148 offset1:214
	ds_write2_b32 v36, v50, v51 offset0:24 offset1:90
	ds_write2_b32 v36, v52, v53 offset0:156 offset1:222
	ds_write2_b32 v37, v54, v55 offset0:32 offset1:98
	ds_write2_b32 v37, v56, v57 offset0:164 offset1:230
	ds_write2_b32 v38, v58, v59 offset0:40 offset1:106
	ds_write2_b32 v38, v60, v61 offset0:172 offset1:238
	ds_write2_b32 v39, v62, v63 offset0:48 offset1:114
	ds_write2_b32 v39, v64, v65 offset0:180 offset1:246
	ds_write2_b32 v40, v66, v67 offset0:56 offset1:122
	ds_write2_b32 v40, v68, v69 offset0:188 offset1:254
	s_waitcnt lgkmcnt(0)
	ds_read2_b32 v[46:47], v32 offset1:8
	ds_read2_b32 v[50:51], v32 offset0:33 offset1:41
	ds_read2_b32 v[52:53], v32 offset0:66 offset1:74
	ds_read2_b32 v[54:55], v32 offset0:99 offset1:107
	s_add_u32 s4, s63, s0
	s_waitcnt lgkmcnt(3)
	v_bfe_u32 v19, v46, 16, 1
	s_addc_u32 s5, s62, 0
	v_add3_u32 v19, v46, v19, s50
	s_waitcnt lgkmcnt(2)
	v_bfe_u32 v21, v50, 16, 1
	ds_read2_b32 v[56:57], v32 offset0:132 offset1:140
	v_lshl_add_u64 v[42:43], s[4:5], 0, v[14:15]
	v_lshrrev_b32_e32 v19, 16, v19
	v_add3_u32 v21, v50, v21, s50
	ds_read2_b32 v[58:59], v32 offset0:165 offset1:173
	v_lshl_add_u64 v[48:49], v[42:43], 0, s[2:3]
	v_and_or_b32 v42, v21, s51, v19
	s_waitcnt lgkmcnt(3)
	v_bfe_u32 v19, v52, 16, 1
	v_add3_u32 v19, v52, v19, s50
	s_waitcnt lgkmcnt(2)
	v_bfe_u32 v21, v54, 16, 1
	ds_read2_b32 v[60:61], v32 offset0:198 offset1:206
	v_lshrrev_b32_e32 v19, 16, v19
	v_add3_u32 v21, v54, v21, s50
	ds_read2_b32 v[62:63], v32 offset0:231 offset1:239
	v_and_or_b32 v43, v21, s51, v19
	s_waitcnt lgkmcnt(3)
	v_bfe_u32 v19, v56, 16, 1
	v_add3_u32 v19, v56, v19, s50
	s_waitcnt lgkmcnt(2)
	v_bfe_u32 v21, v58, 16, 1
	v_lshrrev_b32_e32 v19, 16, v19
	v_add3_u32 v21, v58, v21, s50
	v_and_or_b32 v44, v21, s51, v19
	s_waitcnt lgkmcnt(1)
	v_bfe_u32 v19, v60, 16, 1
	v_add3_u32 v19, v60, v19, s50
	s_waitcnt lgkmcnt(0)
	v_bfe_u32 v21, v62, 16, 1
	v_lshrrev_b32_e32 v19, 16, v19
	v_add3_u32 v21, v62, v21, s50
	v_and_or_b32 v45, v21, s51, v19
	v_mov_b32_e32 v19, v15
	v_lshl_add_u64 v[64:65], v[48:49], 0, v[18:19]
	v_bfe_u32 v19, v47, 16, 1
	v_add3_u32 v19, v47, v19, s50
	v_bfe_u32 v21, v51, 16, 1
	v_lshrrev_b32_e32 v19, 16, v19
	v_add3_u32 v21, v51, v21, s50
	global_store_dwordx4 v[64:65], v[42:45], off sc1
	ds_read2_b32 v[46:47], v32 offset0:16 offset1:24
	v_mov_b32_e32 v23, v15
	v_and_or_b32 v42, v21, s51, v19
	v_bfe_u32 v19, v53, 16, 1
	v_add3_u32 v19, v53, v19, s50
	v_bfe_u32 v21, v55, 16, 1
	v_lshrrev_b32_e32 v19, 16, v19
	v_add3_u32 v21, v55, v21, s50
	v_and_or_b32 v43, v21, s51, v19
	v_bfe_u32 v19, v57, 16, 1
	v_add3_u32 v19, v57, v19, s50
	v_bfe_u32 v21, v59, 16, 1
	v_lshrrev_b32_e32 v19, 16, v19
	v_add3_u32 v21, v59, v21, s50
	v_and_or_b32 v44, v21, s51, v19
	v_bfe_u32 v19, v61, 16, 1
	v_add3_u32 v19, v61, v19, s50
	v_bfe_u32 v21, v63, 16, 1
	v_lshrrev_b32_e32 v19, 16, v19
	v_add3_u32 v21, v63, v21, s50
	v_and_or_b32 v45, v21, s51, v19
	v_mov_b32_e32 v21, v15
	v_lshl_add_u64 v[50:51], v[48:49], 0, v[20:21]
	global_store_dwordx4 v[50:51], v[42:45], off sc1
	ds_read2_b32 v[50:51], v32 offset0:49 offset1:57
	ds_read2_b32 v[52:53], v32 offset0:82 offset1:90
	ds_read2_b32 v[54:55], v32 offset0:115 offset1:123
	s_waitcnt lgkmcnt(3)
	v_bfe_u32 v19, v46, 16, 1
	v_add3_u32 v19, v46, v19, s50
	s_waitcnt lgkmcnt(2)
	v_bfe_u32 v21, v50, 16, 1
	ds_read2_b32 v[56:57], v32 offset0:148 offset1:156
	v_lshrrev_b32_e32 v19, 16, v19
	v_add3_u32 v21, v50, v21, s50
	ds_read2_b32 v[58:59], v32 offset0:181 offset1:189
	v_and_or_b32 v42, v21, s51, v19
	s_waitcnt lgkmcnt(3)
	v_bfe_u32 v19, v52, 16, 1
	v_add3_u32 v19, v52, v19, s50
	s_waitcnt lgkmcnt(2)
	v_bfe_u32 v21, v54, 16, 1
	ds_read2_b32 v[60:61], v32 offset0:214 offset1:222
	v_lshrrev_b32_e32 v19, 16, v19
	v_add3_u32 v21, v54, v21, s50
	ds_read2_b32 v[62:63], v32 offset0:247 offset1:255
	v_and_or_b32 v43, v21, s51, v19
	s_waitcnt lgkmcnt(3)
	v_bfe_u32 v19, v56, 16, 1
	v_add3_u32 v19, v56, v19, s50
	s_waitcnt lgkmcnt(2)
	v_bfe_u32 v21, v58, 16, 1
	v_lshrrev_b32_e32 v19, 16, v19
	v_add3_u32 v21, v58, v21, s50
	v_and_or_b32 v44, v21, s51, v19
	s_waitcnt lgkmcnt(1)
	v_bfe_u32 v19, v60, 16, 1
	v_add3_u32 v19, v60, v19, s50
	s_waitcnt lgkmcnt(0)
	v_bfe_u32 v21, v62, 16, 1
	v_lshrrev_b32_e32 v19, 16, v19
	v_add3_u32 v21, v62, v21, s50
	v_and_or_b32 v45, v21, s51, v19
	v_bfe_u32 v19, v47, 16, 1
	v_add3_u32 v19, v47, v19, s50
	v_bfe_u32 v21, v51, 16, 1
	v_lshl_add_u64 v[64:65], v[48:49], 0, v[22:23]
	v_lshrrev_b32_e32 v19, 16, v19
	v_add3_u32 v21, v51, v21, s50
	global_store_dwordx4 v[64:65], v[42:45], off sc1
	v_mov_b32_e32 v25, v15
	v_lshl_add_u64 v[46:47], v[48:49], 0, v[24:25]
	v_and_or_b32 v42, v21, s51, v19
	v_bfe_u32 v19, v53, 16, 1
	v_add3_u32 v19, v53, v19, s50
	v_bfe_u32 v21, v55, 16, 1
	v_lshrrev_b32_e32 v19, 16, v19
	v_add3_u32 v21, v55, v21, s50
	v_and_or_b32 v43, v21, s51, v19
	v_bfe_u32 v19, v57, 16, 1
	v_add3_u32 v19, v57, v19, s50
	v_bfe_u32 v21, v59, 16, 1
	v_lshrrev_b32_e32 v19, 16, v19
	v_add3_u32 v21, v59, v21, s50
	v_and_or_b32 v44, v21, s51, v19
	v_bfe_u32 v19, v61, 16, 1
	v_add3_u32 v19, v61, v19, s50
	v_bfe_u32 v21, v63, 16, 1
	v_lshrrev_b32_e32 v19, 16, v19
	v_add3_u32 v21, v63, v21, s50
	v_and_or_b32 v45, v21, s51, v19
	global_store_dwordx4 v[46:47], v[42:45], off sc1
	s_waitcnt lgkmcnt(0)

.LBB0_48:
	s_andn2_b64 vcc, exec, s[4:5]
	s_cbranch_vccnz .LBB0_26
	s_mul_hi_i32 s0, s68, 0x2fa0be83
	s_lshr_b32 s4, s0, 31
	s_ashr_i32 s0, s0, 12
	s_add_i32 s0, s0, s4
	s_mul_i32 s4, s0, 0xffffaa00
	s_add_i32 s4, s68, s4
	s_ashr_i32 s5, s0, 1
	s_and_b32 s8, s0, 1
	s_cmp_eq_u32 s8, 0
	s_cselect_b32 s62, s52, s54
	s_mul_hi_i32 s63, s5, 0xac00000
	s_mul_i32 s5, s5, 0xac00000
	s_cselect_b32 s9, s53, s55
	s_add_u32 s5, s62, s5
	s_addc_u32 s63, s9, s63
	s_ashr_i32 s4, s4, 3
	s_mul_hi_i32 s9, s4, 0x2fa0be83
	s_lshr_b32 s62, s9, 31
	s_ashr_i32 s9, s9, 5
	s_add_i32 s62, s9, s62
	s_mul_i32 s9, s62, 0xac
	s_sub_i32 s9, s4, s9
	s_lshl_b32 s4, s9, 6
	s_and_b32 s69, s33, 32
	s_or_b32 s4, s4, s69
	s_cmp_lt_u32 s0, 2
	s_cselect_b32 s0, s61, 0xb000000
	s_add_u32 s0, s64, s0
	s_addc_u32 s69, s65, 0
	s_lshl_b32 s9, s9, 7
	s_and_b32 s9, s9, 0xffffff00
	s_and_b32 s70, s4, 0x60
	s_or_b32 s9, s9, s70
	s_lshl_b32 s8, s8, 7
	s_or_b32 s8, s9, s8
	s_ashr_i32 s9, s8, 31
	s_lshl_b64 s[8:9], s[8:9], 12
	s_add_u32 s0, s0, s8
	s_addc_u32 s8, s69, s9
	s_lshl_b32 s9, s62, 8
	s_and_b32 s62, s33, 0xc0
	s_or_b32 s9, s9, s62
	s_ashr_i32 s62, s9, 31
	s_mul_i32 s70, s9, 0xac00
	s_mul_hi_i32 s69, s9, 0xac00
	s_add_u32 s70, s5, s70
	s_addc_u32 s63, s63, s69
	s_ashr_i32 s5, s4, 31
	s_lshl_b64 s[4:5], s[4:5], 2
	s_add_u32 s4, s70, s4
	s_addc_u32 s5, s63, s5
	s_add_u32 s70, s4, 0x15800
	s_addc_u32 s71, s5, 0
	global_load_dword v19, v33, s[4:5] nt
	global_load_dword v21, v33, s[70:71] nt
	s_add_u32 s70, s4, 0x2b000
	s_addc_u32 s71, s5, 0
	global_load_dword v23, v33, s[70:71] nt
	s_add_u32 s70, s4, 0x40800
	s_addc_u32 s71, s5, 0
	global_load_dword v25, v33, s[70:71] nt
	s_add_u32 s70, s4, 0x56000
	s_addc_u32 s71, s5, 0
	global_load_dword v42, v33, s[70:71] nt
	s_add_u32 s70, s4, 0x6b800
	s_addc_u32 s71, s5, 0
	global_load_dword v43, v33, s[70:71] nt
	s_add_u32 s70, s4, 0x81000
	s_addc_u32 s71, s5, 0
	global_load_dword v44, v33, s[70:71] nt
	s_add_u32 s70, s4, 0x96800
	s_addc_u32 s71, s5, 0
	global_load_dword v45, v33, s[70:71] nt
	s_add_u32 s70, s4, 0xac000
	s_addc_u32 s71, s5, 0
	global_load_dword v46, v33, s[70:71] nt
	s_add_u32 s70, s4, 0xc1800
	s_addc_u32 s71, s5, 0
	global_load_dword v47, v33, s[70:71] nt
	s_add_u32 s70, s4, 0xd7000
	s_addc_u32 s71, s5, 0
	global_load_dword v48, v33, s[70:71] nt
	s_add_u32 s70, s4, 0xec800
	s_addc_u32 s71, s5, 0
	global_load_dword v49, v33, s[70:71] nt
	s_add_u32 s70, s4, 0x102000
	s_addc_u32 s71, s5, 0
	global_load_dword v50, v33, s[70:71] nt
	s_add_u32 s70, s4, 0x117800
	s_addc_u32 s71, s5, 0
	global_load_dword v51, v33, s[70:71] nt
	s_add_u32 s70, s4, 0x12d000
	s_addc_u32 s71, s5, 0
	global_load_dword v52, v33, s[70:71] nt
	s_add_u32 s70, s4, 0x142800
	s_addc_u32 s71, s5, 0
	global_load_dword v53, v33, s[70:71] nt
	s_add_u32 s70, s4, 0x158000
	s_addc_u32 s71, s5, 0
	global_load_dword v54, v33, s[70:71] nt
	s_add_u32 s70, s4, 0x16d800
	s_addc_u32 s71, s5, 0
	global_load_dword v55, v33, s[70:71] nt
	s_add_u32 s70, s4, 0x183000
	s_addc_u32 s71, s5, 0
	global_load_dword v56, v33, s[70:71] nt
	s_add_u32 s70, s4, 0x198800
	s_addc_u32 s71, s5, 0
	global_load_dword v57, v33, s[70:71] nt
	s_add_u32 s70, s4, 0x1ae000
	s_addc_u32 s71, s5, 0
	global_load_dword v58, v33, s[70:71] nt
	s_add_u32 s70, s4, 0x1c3800
	s_addc_u32 s71, s5, 0
	global_load_dword v59, v33, s[70:71] nt
	s_add_u32 s70, s4, 0x1d9000
	s_addc_u32 s71, s5, 0
	global_load_dword v60, v33, s[70:71] nt
	s_add_u32 s70, s4, 0x1ee800
	s_addc_u32 s71, s5, 0
	global_load_dword v61, v33, s[70:71] nt
	s_add_u32 s70, s4, 0x204000
	s_addc_u32 s71, s5, 0
	global_load_dword v62, v33, s[70:71] nt
	s_add_u32 s70, s4, 0x219800
	s_addc_u32 s71, s5, 0
	global_load_dword v63, v33, s[70:71] nt
	s_add_u32 s70, s4, 0x22f000
	s_addc_u32 s71, s5, 0
	global_load_dword v64, v33, s[70:71] nt
	s_add_u32 s70, s4, 0x244800
	s_addc_u32 s71, s5, 0
	global_load_dword v65, v33, s[70:71] nt
	s_add_u32 s70, s4, 0x25a000
	s_addc_u32 s71, s5, 0
	global_load_dword v66, v33, s[70:71] nt
	s_add_u32 s70, s4, 0x26f800
	s_addc_u32 s71, s5, 0
	global_load_dword v67, v33, s[70:71] nt
	s_add_u32 s70, s4, 0x285000
	s_addc_u32 s71, s5, 0
	s_add_u32 s4, s4, 0x29a800
	global_load_dword v68, v33, s[70:71] nt
	s_addc_u32 s5, s5, 0
	global_load_dword v69, v33, s[4:5] nt
	s_waitcnt vmcnt(0)
	s_add_u32 s4, s0, s9
	ds_write2_b32 v30, v19, v21 offset1:66
	ds_write2_b32 v30, v23, v25 offset0:132 offset1:198
	ds_write2_b32 v34, v42, v43 offset0:8 offset1:74
	ds_write2_b32 v34, v44, v45 offset0:140 offset1:206
	ds_write2_b32 v35, v46, v47 offset0:16 offset1:82
	ds_write2_b32 v35, v48, v49 offset0:148 offset1:214
	ds_write2_b32 v36, v50, v51 offset0:24 offset1:90
	ds_write2_b32 v36, v52, v53 offset0:156 offset1:222
	ds_write2_b32 v37, v54, v55 offset0:32 offset1:98
	ds_write2_b32 v37, v56, v57 offset0:164 offset1:230
	ds_write2_b32 v38, v58, v59 offset0:40 offset1:106
	ds_write2_b32 v38, v60, v61 offset0:172 offset1:238
	ds_write2_b32 v39, v62, v63 offset0:48 offset1:114
	ds_write2_b32 v39, v64, v65 offset0:180 offset1:246
	ds_write2_b32 v40, v66, v67 offset0:56 offset1:122
	ds_write2_b32 v40, v68, v69 offset0:188 offset1:254
	s_waitcnt lgkmcnt(0)
	ds_read2_b32 v[48:49], v31 offset1:16
	ds_read2_b32 v[50:51], v31 offset0:33 offset1:49
	ds_read2_b32 v[52:53], v31 offset0:66 offset1:82
	ds_read2_b32 v[54:55], v31 offset0:99 offset1:115
	ds_read2_b32 v[56:57], v31 offset0:132 offset1:148
	ds_read2_b32 v[58:59], v31 offset0:165 offset1:181
	ds_read2_b32 v[60:61], v31 offset0:198 offset1:214
	ds_read2_b32 v[62:63], v31 offset0:231 offset1:247
	ds_read2_b32 v[64:65], v41 offset0:8 offset1:24
	ds_read2_b32 v[66:67], v41 offset0:41 offset1:57
	ds_read2_b32 v[68:69], v41 offset0:74 offset1:90
	ds_read2_b32 v[70:71], v41 offset0:107 offset1:123
	ds_read2_b32 v[72:73], v41 offset0:140 offset1:156
	ds_read2_b32 v[74:75], v41 offset0:173 offset1:189
	ds_read2_b32 v[76:77], v41 offset0:206 offset1:222
	ds_read2_b32 v[78:79], v41 offset0:239 offset1:255
	s_addc_u32 s5, s8, s62
	v_mov_b32_e32 v42, 0
	v_mov_b32_e32 v43, 0
	v_mov_b32_e32 v44, 0
	v_mov_b32_e32 v45, 0
	v_lshl_add_u64 v[46:47], s[4:5], 0, v[2:3]
	s_waitcnt lgkmcnt(14)
	v_cvt_scalef32_pk_fp8_f32 v42, v48, v50, s49
	s_waitcnt lgkmcnt(10)
	v_cvt_scalef32_pk_fp8_f32 v43, v56, v58, s49
	s_waitcnt lgkmcnt(6)
	v_cvt_scalef32_pk_fp8_f32 v44, v64, v66, s49
	s_waitcnt lgkmcnt(2)
	v_cvt_scalef32_pk_fp8_f32 v45, v72, v74, s49
	v_cvt_scalef32_pk_fp8_f32 v42, v52, v54, s49 op_sel:[0,0,0,1]
	v_cvt_scalef32_pk_fp8_f32 v43, v60, v62, s49 op_sel:[0,0,0,1]
	v_cvt_scalef32_pk_fp8_f32 v44, v68, v70, s49 op_sel:[0,0,0,1]
	s_waitcnt lgkmcnt(0)
	v_cvt_scalef32_pk_fp8_f32 v45, v76, v78, s49 op_sel:[0,0,0,1]
	v_lshl_add_u64 v[80:81], v[46:47], 0, v[4:5]
	global_store_dwordx4 v[80:81], v[42:45], off sc1
	v_lshl_add_u64 v[46:47], v[46:47], 0, v[6:7]
	s_nop 0
	v_mov_b32_e32 v42, 0
	v_mov_b32_e32 v43, 0
	v_mov_b32_e32 v44, 0
	v_mov_b32_e32 v45, 0
	v_cvt_scalef32_pk_fp8_f32 v42, v49, v51, s49
	v_cvt_scalef32_pk_fp8_f32 v43, v57, v59, s49
	v_cvt_scalef32_pk_fp8_f32 v44, v65, v67, s49
	v_cvt_scalef32_pk_fp8_f32 v45, v73, v75, s49
	v_cvt_scalef32_pk_fp8_f32 v42, v53, v55, s49 op_sel:[0,0,0,1]
	v_cvt_scalef32_pk_fp8_f32 v43, v61, v63, s49 op_sel:[0,0,0,1]
	v_cvt_scalef32_pk_fp8_f32 v44, v69, v71, s49 op_sel:[0,0,0,1]
	v_cvt_scalef32_pk_fp8_f32 v45, v77, v79, s49 op_sel:[0,0,0,1]
	global_store_dwordx4 v[46:47], v[42:45], off sc1
	s_waitcnt lgkmcnt(0)
	s_branch .LBB0_26

.LBB0_52:
	v_add_u32_e32 v10, s0, v10
	v_cmp_lt_i32_e32 vcc, s1, v10
	global_store_dwordx4 v[8:9], v[2:5], off sc1
	s_or_b64 s[6:7], vcc, s[6:7]
	v_lshl_add_u64 v[8:9], v[8:9], 0, s[4:5]
	s_andn2_b64 exec, exec, s[6:7]
	s_cbranch_execnz .LBB0_52
